# zero64
# speedup vs baseline: 1.0133x; 1.0054x over previous
; #define WAIT_V(n) asm volatile("s_waitcnt vmcnt(" #n ")" ::: "memory")
; #define BAR __builtin_amdgcn_s_barrier()
; template <int EPI>
; __device__ __forceinline__ void gemm_phase(const u16* __restrict__ A, const u16* __restrict__ Bt, const int K,
;                                            const int nN, char* shm, const EpiArgs& ea) {
;     ...
;     f32x4 acc[2][2][4][2];
; #pragma unroll
;     for (int a = 0; a < 2; ++a)
; #pragma unroll
;       for (int b = 0; b < 2; ++b)
; #pragma unroll
;         for (int m = 0; m < 4; ++m)
; #pragma unroll
;           for (int n = 0; n < 2; ++n) acc[a][b][m][n] = f32x4{0.f, 0.f, 0.f, 0.f};
;     bf16x8 At[4][2], B0[2][2], B1[2][2];
;     WAIT_V(0);
;     if (wr == 1) BAR;
;     BAR;
.LBB0_171:
	s_add_i32 s6, s66, 0x80
	s_lshr_b32 s67, s6, 7
	s_add_i32 s6, s7, 0x80
	s_lshr_b32 s70, s7, 7
	s_lshr_b32 s69, s66, 7
	s_lshr_b32 s68, s6, 7
	s_mul_i32 s68, s68, 0x84000
	s_mul_i32 s69, s69, 0x84000
	s_mul_i32 s70, s70, 0x84000
	s_mul_i32 s67, s67, 0x84000
	s_mov_b32 s71, -2
	s_mov_b32 s72, 0
	v_mov_b64_e32 v[0:1], 0
	v_mov_b64_e32 v[2:3], 0
	v_mov_b64_e32 v[4:5], 0
	v_mov_b64_e32 v[6:7], 0
	v_mov_b64_e32 v[8:9], 0
	v_mov_b64_e32 v[10:11], 0
	v_mov_b64_e32 v[12:13], 0
	v_mov_b64_e32 v[14:15], 0
	v_mov_b64_e32 v[16:17], 0
	v_mov_b64_e32 v[18:19], 0
	v_mov_b64_e32 v[20:21], 0
	v_mov_b64_e32 v[22:23], 0
	v_mov_b64_e32 v[24:25], 0
	v_mov_b64_e32 v[26:27], 0
	v_mov_b64_e32 v[28:29], 0
	v_mov_b64_e32 v[30:31], 0
	v_mov_b64_e32 v[32:33], 0
	v_mov_b64_e32 v[34:35], 0
	v_mov_b64_e32 v[36:37], 0
	v_mov_b64_e32 v[38:39], 0
	v_mov_b64_e32 v[40:41], 0
	v_mov_b64_e32 v[42:43], 0
	v_mov_b64_e32 v[44:45], 0
	v_mov_b64_e32 v[46:47], 0
	v_mov_b64_e32 v[48:49], 0
	v_mov_b64_e32 v[50:51], 0
	v_mov_b64_e32 v[52:53], 0
	v_mov_b64_e32 v[54:55], 0
	v_mov_b64_e32 v[56:57], 0
	v_mov_b64_e32 v[58:59], 0
	v_mov_b64_e32 v[60:61], 0
	v_mov_b64_e32 v[62:63], 0
	v_mov_b64_e32 v[64:65], 0
	v_mov_b64_e32 v[66:67], 0
	v_mov_b64_e32 v[68:69], 0
	v_mov_b64_e32 v[70:71], 0
	v_mov_b64_e32 v[72:73], 0
	v_mov_b64_e32 v[74:75], 0
	v_mov_b64_e32 v[76:77], 0
	v_mov_b64_e32 v[78:79], 0
	v_mov_b64_e32 v[80:81], 0
	v_mov_b64_e32 v[82:83], 0
	v_mov_b64_e32 v[84:85], 0
	v_mov_b64_e32 v[86:87], 0
	v_mov_b64_e32 v[88:89], 0
	v_mov_b64_e32 v[90:91], 0
	v_mov_b64_e32 v[92:93], 0
	v_mov_b64_e32 v[94:95], 0
	v_mov_b64_e32 v[96:97], 0
	v_mov_b64_e32 v[98:99], 0
	v_mov_b64_e32 v[100:101], 0
	v_mov_b64_e32 v[102:103], 0
	v_mov_b64_e32 v[104:105], 0
	v_mov_b64_e32 v[106:107], 0
	v_mov_b64_e32 v[108:109], 0
	v_mov_b64_e32 v[110:111], 0
	v_mov_b64_e32 v[112:113], 0
	v_mov_b64_e32 v[114:115], 0
	v_mov_b64_e32 v[116:117], 0
	v_mov_b64_e32 v[118:119], 0
	v_mov_b64_e32 v[120:121], 0
	v_mov_b64_e32 v[122:123], 0
	v_mov_b64_e32 v[124:125], 0
	v_mov_b64_e32 v[126:127], 0
	s_barrier
	s_barrier

; #define WAIT_V(n) asm volatile("s_waitcnt vmcnt(" #n ")" ::: "memory")
; #define BAR __builtin_amdgcn_s_barrier()
; template <int EPI>
; __device__ __forceinline__ void gemm_phase(const u16* __restrict__ A, const u16* __restrict__ Bt, const int K,
;                                            const int nN, char* shm, const EpiArgs& ea) {
;     ...
;     f32x4 acc[2][2][4][2];
; #pragma unroll
;     for (int a = 0; a < 2; ++a)
; #pragma unroll
;       for (int b = 0; b < 2; ++b)
; #pragma unroll
;         for (int m = 0; m < 4; ++m)
; #pragma unroll
;           for (int n = 0; n < 2; ++n) acc[a][b][m][n] = f32x4{0.f, 0.f, 0.f, 0.f};
;     bf16x8 At[4][2], B0[2][2], B1[2][2];
;     WAIT_V(0);
;     if (wr == 1) BAR;
;     BAR;
.LBB0_230:
	s_add_i32 s26, s69, 0x80
	s_lshr_b32 s70, s26, 7
	s_add_i32 s26, s33, 0x80
	s_lshr_b32 s73, s33, 7
	s_lshr_b32 s72, s69, 7
	s_lshr_b32 s71, s26, 7
	s_mul_i32 s71, s71, 0x164000
	s_mul_i32 s72, s72, 0x164000
	s_mul_i32 s73, s73, 0x164000
	s_mul_i32 s70, s70, 0x164000
	s_mov_b32 s74, -2
	s_mov_b32 s75, 0
	s_waitcnt vmcnt(0)
	v_mov_b64_e32 v[0:1], 0
	v_mov_b64_e32 v[2:3], 0
	v_mov_b64_e32 v[4:5], 0
	v_mov_b64_e32 v[6:7], 0
	v_mov_b64_e32 v[8:9], 0
	v_mov_b64_e32 v[10:11], 0
	v_mov_b64_e32 v[12:13], 0
	v_mov_b64_e32 v[14:15], 0
	v_mov_b64_e32 v[16:17], 0
	v_mov_b64_e32 v[18:19], 0
	v_mov_b64_e32 v[20:21], 0
	v_mov_b64_e32 v[22:23], 0
	v_mov_b64_e32 v[24:25], 0
	v_mov_b64_e32 v[26:27], 0
	v_mov_b64_e32 v[28:29], 0
	v_mov_b64_e32 v[30:31], 0
	v_mov_b64_e32 v[32:33], 0
	v_mov_b64_e32 v[34:35], 0
	v_mov_b64_e32 v[36:37], 0
	v_mov_b64_e32 v[38:39], 0
	v_mov_b64_e32 v[40:41], 0
	v_mov_b64_e32 v[42:43], 0
	v_mov_b64_e32 v[44:45], 0
	v_mov_b64_e32 v[46:47], 0
	v_mov_b64_e32 v[48:49], 0
	v_mov_b64_e32 v[50:51], 0
	v_mov_b64_e32 v[52:53], 0
	v_mov_b64_e32 v[54:55], 0
	v_mov_b64_e32 v[56:57], 0
	v_mov_b64_e32 v[58:59], 0
	v_mov_b64_e32 v[60:61], 0
	v_mov_b64_e32 v[62:63], 0
	v_mov_b64_e32 v[64:65], 0
	v_mov_b64_e32 v[66:67], 0
	v_mov_b64_e32 v[68:69], 0
	v_mov_b64_e32 v[70:71], 0
	v_mov_b64_e32 v[72:73], 0
	v_mov_b64_e32 v[74:75], 0
	v_mov_b64_e32 v[76:77], 0
	v_mov_b64_e32 v[78:79], 0
	v_mov_b64_e32 v[80:81], 0
	v_mov_b64_e32 v[82:83], 0
	v_mov_b64_e32 v[84:85], 0
	v_mov_b64_e32 v[86:87], 0
	v_mov_b64_e32 v[88:89], 0
	v_mov_b64_e32 v[90:91], 0
	v_mov_b64_e32 v[92:93], 0
	v_mov_b64_e32 v[94:95], 0
	v_mov_b64_e32 v[96:97], 0
	v_mov_b64_e32 v[98:99], 0
	v_mov_b64_e32 v[100:101], 0
	v_mov_b64_e32 v[102:103], 0
	v_mov_b64_e32 v[104:105], 0
	v_mov_b64_e32 v[106:107], 0
	v_mov_b64_e32 v[108:109], 0
	v_mov_b64_e32 v[110:111], 0
	v_mov_b64_e32 v[112:113], 0
	v_mov_b64_e32 v[114:115], 0
	v_mov_b64_e32 v[116:117], 0
	v_mov_b64_e32 v[118:119], 0
	v_mov_b64_e32 v[120:121], 0
	v_mov_b64_e32 v[122:123], 0
	v_mov_b64_e32 v[124:125], 0
	v_mov_b64_e32 v[126:127], 0
	s_barrier
	s_barrier

; #define WAIT_V(n) asm volatile("s_waitcnt vmcnt(" #n ")" ::: "memory")
; #define BAR __builtin_amdgcn_s_barrier()
; template <int EPI>
; __device__ __forceinline__ void gemm_phase(const u16* __restrict__ A, const u16* __restrict__ Bt, const int K,
;                                            const int nN, char* shm, const EpiArgs& ea) {
;     ...
;     f32x4 acc[2][2][4][2];
; #pragma unroll
;     for (int a = 0; a < 2; ++a)
; #pragma unroll
;       for (int b = 0; b < 2; ++b)
; #pragma unroll
;         for (int m = 0; m < 4; ++m)
; #pragma unroll
;           for (int n = 0; n < 2; ++n) acc[a][b][m][n] = f32x4{0.f, 0.f, 0.f, 0.f};
;     bf16x8 At[4][2], B0[2][2], B1[2][2];
;     WAIT_V(0);
;     if (wr == 1) BAR;
;     BAR;
.LBB0_305:
	s_add_i32 s26, s33, 0x80
	s_lshr_b32 s72, s26, 7
	s_add_i32 s26, s42, 0x80
	s_lshr_b32 s74, s42, 7
	s_lshr_b32 s73, s33, 7
	s_lshr_b32 s43, s26, 7
	s_mul_i32 s43, s43, 0x84000
	s_mul_i32 s73, s73, 0x84000
	s_mul_i32 s74, s74, 0x84000
	s_mul_i32 s72, s72, 0x84000
	s_mov_b32 s75, -2
	s_mov_b32 s78, 0
	s_waitcnt vmcnt(0)
	v_mov_b64_e32 v[0:1], 0
	v_mov_b64_e32 v[2:3], 0
	v_mov_b64_e32 v[4:5], 0
	v_mov_b64_e32 v[6:7], 0
	v_mov_b64_e32 v[8:9], 0
	v_mov_b64_e32 v[10:11], 0
	v_mov_b64_e32 v[12:13], 0
	v_mov_b64_e32 v[14:15], 0
	v_mov_b64_e32 v[16:17], 0
	v_mov_b64_e32 v[18:19], 0
	v_mov_b64_e32 v[20:21], 0
	v_mov_b64_e32 v[22:23], 0
	v_mov_b64_e32 v[24:25], 0
	v_mov_b64_e32 v[26:27], 0
	v_mov_b64_e32 v[28:29], 0
	v_mov_b64_e32 v[30:31], 0
	v_mov_b64_e32 v[32:33], 0
	v_mov_b64_e32 v[34:35], 0
	v_mov_b64_e32 v[36:37], 0
	v_mov_b64_e32 v[38:39], 0
	v_mov_b64_e32 v[40:41], 0
	v_mov_b64_e32 v[42:43], 0
	v_mov_b64_e32 v[44:45], 0
	v_mov_b64_e32 v[46:47], 0
	v_mov_b64_e32 v[48:49], 0
	v_mov_b64_e32 v[50:51], 0
	v_mov_b64_e32 v[52:53], 0
	v_mov_b64_e32 v[54:55], 0
	v_mov_b64_e32 v[56:57], 0
	v_mov_b64_e32 v[58:59], 0
	v_mov_b64_e32 v[60:61], 0
	v_mov_b64_e32 v[62:63], 0
	v_mov_b64_e32 v[64:65], 0
	v_mov_b64_e32 v[66:67], 0
	v_mov_b64_e32 v[68:69], 0
	v_mov_b64_e32 v[70:71], 0
	v_mov_b64_e32 v[72:73], 0
	v_mov_b64_e32 v[74:75], 0
	v_mov_b64_e32 v[76:77], 0
	v_mov_b64_e32 v[78:79], 0
	v_mov_b64_e32 v[80:81], 0
	v_mov_b64_e32 v[82:83], 0
	v_mov_b64_e32 v[84:85], 0
	v_mov_b64_e32 v[86:87], 0
	v_mov_b64_e32 v[88:89], 0
	v_mov_b64_e32 v[90:91], 0
	v_mov_b64_e32 v[92:93], 0
	v_mov_b64_e32 v[94:95], 0
	v_mov_b64_e32 v[96:97], 0
	v_mov_b64_e32 v[98:99], 0
	v_mov_b64_e32 v[100:101], 0
	v_mov_b64_e32 v[102:103], 0
	v_mov_b64_e32 v[104:105], 0
	v_mov_b64_e32 v[106:107], 0
	v_mov_b64_e32 v[108:109], 0
	v_mov_b64_e32 v[110:111], 0
	v_mov_b64_e32 v[112:113], 0
	v_mov_b64_e32 v[114:115], 0
	v_mov_b64_e32 v[116:117], 0
	v_mov_b64_e32 v[118:119], 0
	v_mov_b64_e32 v[120:121], 0
	v_mov_b64_e32 v[122:123], 0
	v_mov_b64_e32 v[124:125], 0
	v_mov_b64_e32 v[126:127], 0
	s_barrier
	s_barrier

; #define WAIT_V(n) asm volatile("s_waitcnt vmcnt(" #n ")" ::: "memory")
; #define BAR __builtin_amdgcn_s_barrier()
; template <int EPI>
; __device__ __forceinline__ void gemm_phase(const u16* __restrict__ A, const u16* __restrict__ Bt, const int K,
;                                            const int nN, char* shm, const EpiArgs& ea) {
;     ...
;     f32x4 acc[2][2][4][2];
; #pragma unroll
;     for (int a = 0; a < 2; ++a)
; #pragma unroll
;       for (int b = 0; b < 2; ++b)
; #pragma unroll
;         for (int m = 0; m < 4; ++m)
; #pragma unroll
;           for (int n = 0; n < 2; ++n) acc[a][b][m][n] = f32x4{0.f, 0.f, 0.f, 0.f};
;     bf16x8 At[4][2], B0[2][2], B1[2][2];
;     WAIT_V(0);
;     if (wr == 1) BAR;
;     BAR;
.LBB0_491:
	s_add_i32 s10, s58, 0x80
	s_lshr_b32 s59, s10, 7
	s_add_i32 s10, s33, 0x80
	s_lshr_b32 s62, s33, 7
	s_lshr_b32 s61, s58, 7
	s_lshr_b32 s60, s10, 7
	s_mul_i32 s60, s60, 0x84000
	s_mul_i32 s61, s61, 0x84000
	s_mul_i32 s62, s62, 0x84000
	s_mul_i32 s59, s59, 0x84000
	s_mov_b32 s63, -2
	s_mov_b32 s64, 0
	s_waitcnt vmcnt(0)
	v_mov_b64_e32 v[0:1], 0
	v_mov_b64_e32 v[2:3], 0
	v_mov_b64_e32 v[4:5], 0
	v_mov_b64_e32 v[6:7], 0
	v_mov_b64_e32 v[8:9], 0
	v_mov_b64_e32 v[10:11], 0
	v_mov_b64_e32 v[12:13], 0
	v_mov_b64_e32 v[14:15], 0
	v_mov_b64_e32 v[16:17], 0
	v_mov_b64_e32 v[18:19], 0
	v_mov_b64_e32 v[20:21], 0
	v_mov_b64_e32 v[22:23], 0
	v_mov_b64_e32 v[24:25], 0
	v_mov_b64_e32 v[26:27], 0
	v_mov_b64_e32 v[28:29], 0
	v_mov_b64_e32 v[30:31], 0
	v_mov_b64_e32 v[32:33], 0
	v_mov_b64_e32 v[34:35], 0
	v_mov_b64_e32 v[36:37], 0
	v_mov_b64_e32 v[38:39], 0
	v_mov_b64_e32 v[40:41], 0
	v_mov_b64_e32 v[42:43], 0
	v_mov_b64_e32 v[44:45], 0
	v_mov_b64_e32 v[46:47], 0
	v_mov_b64_e32 v[48:49], 0
	v_mov_b64_e32 v[50:51], 0
	v_mov_b64_e32 v[52:53], 0
	v_mov_b64_e32 v[54:55], 0
	v_mov_b64_e32 v[56:57], 0
	v_mov_b64_e32 v[58:59], 0
	v_mov_b64_e32 v[60:61], 0
	v_mov_b64_e32 v[62:63], 0
	v_mov_b64_e32 v[64:65], 0
	v_mov_b64_e32 v[66:67], 0
	v_mov_b64_e32 v[68:69], 0
	v_mov_b64_e32 v[70:71], 0
	v_mov_b64_e32 v[72:73], 0
	v_mov_b64_e32 v[74:75], 0
	v_mov_b64_e32 v[76:77], 0
	v_mov_b64_e32 v[78:79], 0
	v_mov_b64_e32 v[80:81], 0
	v_mov_b64_e32 v[82:83], 0
	v_mov_b64_e32 v[84:85], 0
	v_mov_b64_e32 v[86:87], 0
	v_mov_b64_e32 v[88:89], 0
	v_mov_b64_e32 v[90:91], 0
	v_mov_b64_e32 v[92:93], 0
	v_mov_b64_e32 v[94:95], 0
	v_mov_b64_e32 v[96:97], 0
	v_mov_b64_e32 v[98:99], 0
	v_mov_b64_e32 v[100:101], 0
	v_mov_b64_e32 v[102:103], 0
	v_mov_b64_e32 v[104:105], 0
	v_mov_b64_e32 v[106:107], 0
	v_mov_b64_e32 v[108:109], 0
	v_mov_b64_e32 v[110:111], 0
	v_mov_b64_e32 v[112:113], 0
	v_mov_b64_e32 v[114:115], 0
	v_mov_b64_e32 v[116:117], 0
	v_mov_b64_e32 v[118:119], 0
	v_mov_b64_e32 v[120:121], 0
	v_mov_b64_e32 v[122:123], 0
	v_mov_b64_e32 v[124:125], 0
	v_mov_b64_e32 v[126:127], 0
	s_barrier
	s_barrier

; #define WAIT_V(n) asm volatile("s_waitcnt vmcnt(" #n ")" ::: "memory")
; #define BAR __builtin_amdgcn_s_barrier()
; template <int EPI>
; __device__ __forceinline__ void gemm_phase(const u16* __restrict__ A, const u16* __restrict__ Bt, const int K,
;                                            const int nN, char* shm, const EpiArgs& ea) {
;     ...
;     f32x4 acc[2][2][4][2];
; #pragma unroll
;     for (int a = 0; a < 2; ++a)
; #pragma unroll
;       for (int b = 0; b < 2; ++b)
; #pragma unroll
;         for (int m = 0; m < 4; ++m)
; #pragma unroll
;           for (int n = 0; n < 2; ++n) acc[a][b][m][n] = f32x4{0.f, 0.f, 0.f, 0.f};
;     bf16x8 At[4][2], B0[2][2], B1[2][2];
;     WAIT_V(0);
;     if (wr == 1) BAR;
;     BAR;
.LBB0_564:
	s_add_i32 s6, s56, 0x80
	s_lshr_b32 s58, s6, 7
	s_add_i32 s6, s57, 0x80
	s_lshr_b32 s61, s57, 7
	s_lshr_b32 s60, s56, 7
	s_lshr_b32 s59, s6, 7
	s_mul_i32 s59, s59, 0x84000
	s_mul_i32 s60, s60, 0x84000
	s_mul_i32 s61, s61, 0x84000
	s_mul_i32 s58, s58, 0x84000
	s_mov_b32 s62, -2
	s_mov_b32 s63, 0
	s_waitcnt vmcnt(14)
	v_mov_b64_e32 v[0:1], 0
	v_mov_b64_e32 v[2:3], 0
	v_mov_b64_e32 v[4:5], 0
	v_mov_b64_e32 v[6:7], 0
	v_mov_b64_e32 v[8:9], 0
	v_mov_b64_e32 v[10:11], 0
	v_mov_b64_e32 v[12:13], 0
	v_mov_b64_e32 v[14:15], 0
	v_mov_b64_e32 v[16:17], 0
	v_mov_b64_e32 v[18:19], 0
	v_mov_b64_e32 v[20:21], 0
	v_mov_b64_e32 v[22:23], 0
	v_mov_b64_e32 v[24:25], 0
	v_mov_b64_e32 v[26:27], 0
	v_mov_b64_e32 v[28:29], 0
	v_mov_b64_e32 v[30:31], 0
	v_mov_b64_e32 v[32:33], 0
	v_mov_b64_e32 v[34:35], 0
	v_mov_b64_e32 v[36:37], 0
	v_mov_b64_e32 v[38:39], 0
	v_mov_b64_e32 v[40:41], 0
	v_mov_b64_e32 v[42:43], 0
	v_mov_b64_e32 v[44:45], 0
	v_mov_b64_e32 v[46:47], 0
	v_mov_b64_e32 v[48:49], 0
	v_mov_b64_e32 v[50:51], 0
	v_mov_b64_e32 v[52:53], 0
	v_mov_b64_e32 v[54:55], 0
	v_mov_b64_e32 v[56:57], 0
	v_mov_b64_e32 v[58:59], 0
	v_mov_b64_e32 v[60:61], 0
	v_mov_b64_e32 v[62:63], 0
	v_mov_b64_e32 v[64:65], 0
	v_mov_b64_e32 v[66:67], 0
	v_mov_b64_e32 v[68:69], 0
	v_mov_b64_e32 v[70:71], 0
	v_mov_b64_e32 v[72:73], 0
	v_mov_b64_e32 v[74:75], 0
	v_mov_b64_e32 v[76:77], 0
	v_mov_b64_e32 v[78:79], 0
	v_mov_b64_e32 v[80:81], 0
	v_mov_b64_e32 v[82:83], 0
	v_mov_b64_e32 v[84:85], 0
	v_mov_b64_e32 v[86:87], 0
	v_mov_b64_e32 v[88:89], 0
	v_mov_b64_e32 v[90:91], 0
	v_mov_b64_e32 v[92:93], 0
	v_mov_b64_e32 v[94:95], 0
	v_mov_b64_e32 v[96:97], 0
	v_mov_b64_e32 v[98:99], 0
	v_mov_b64_e32 v[100:101], 0
	v_mov_b64_e32 v[102:103], 0
	v_mov_b64_e32 v[104:105], 0
	v_mov_b64_e32 v[106:107], 0
	v_mov_b64_e32 v[108:109], 0
	v_mov_b64_e32 v[110:111], 0
	v_mov_b64_e32 v[112:113], 0
	v_mov_b64_e32 v[114:115], 0
	v_mov_b64_e32 v[116:117], 0
	v_mov_b64_e32 v[118:119], 0
	v_mov_b64_e32 v[120:121], 0
	v_mov_b64_e32 v[122:123], 0
	v_mov_b64_e32 v[124:125], 0
	v_mov_b64_e32 v[126:127], 0
	s_barrier
	s_barrier

; #define WAIT_V(n) asm volatile("s_waitcnt vmcnt(" #n ")" ::: "memory")
; #define BAR __builtin_amdgcn_s_barrier()
; template <int EPI>
; __device__ __forceinline__ void gemm_phase(const u16* __restrict__ A, const u16* __restrict__ Bt, const int K,
;                                            const int nN, char* shm, const EpiArgs& ea) {
;     ...
;     f32x4 acc[2][2][4][2];
; #pragma unroll
;     for (int a = 0; a < 2; ++a)
; #pragma unroll
;       for (int b = 0; b < 2; ++b)
; #pragma unroll
;         for (int m = 0; m < 4; ++m)
; #pragma unroll
;           for (int n = 0; n < 2; ++n) acc[a][b][m][n] = f32x4{0.f, 0.f, 0.f, 0.f};
;     bf16x8 At[4][2], B0[2][2], B1[2][2];
;     WAIT_V(0);
;     if (wr == 1) BAR;
;     BAR;
.LBB0_630:
	s_add_i32 s6, s33, 0x80
	s_lshr_b32 s48, s6, 7
	s_add_i32 s6, s47, 0x80
	s_lshr_b32 s51, s47, 7
	s_lshr_b32 s50, s33, 7
	s_lshr_b32 s49, s6, 7
	s_mul_i32 s49, s49, 0x164000
	s_mul_i32 s50, s50, 0x164000
	s_mul_i32 s51, s51, 0x164000
	s_mul_i32 s48, s48, 0x164000
	s_mov_b32 s52, -2
	s_mov_b32 s53, 0
	s_waitcnt vmcnt(14)
	v_mov_b64_e32 v[0:1], 0
	v_mov_b64_e32 v[2:3], 0
	v_mov_b64_e32 v[4:5], 0
	v_mov_b64_e32 v[6:7], 0
	v_mov_b64_e32 v[8:9], 0
	v_mov_b64_e32 v[10:11], 0
	v_mov_b64_e32 v[12:13], 0
	v_mov_b64_e32 v[14:15], 0
	v_mov_b64_e32 v[16:17], 0
	v_mov_b64_e32 v[18:19], 0
	v_mov_b64_e32 v[20:21], 0
	v_mov_b64_e32 v[22:23], 0
	v_mov_b64_e32 v[24:25], 0
	v_mov_b64_e32 v[26:27], 0
	v_mov_b64_e32 v[28:29], 0
	v_mov_b64_e32 v[30:31], 0
	v_mov_b64_e32 v[32:33], 0
	v_mov_b64_e32 v[34:35], 0
	v_mov_b64_e32 v[36:37], 0
	v_mov_b64_e32 v[38:39], 0
	v_mov_b64_e32 v[40:41], 0
	v_mov_b64_e32 v[42:43], 0
	v_mov_b64_e32 v[44:45], 0
	v_mov_b64_e32 v[46:47], 0
	v_mov_b64_e32 v[48:49], 0
	v_mov_b64_e32 v[50:51], 0
	v_mov_b64_e32 v[52:53], 0
	v_mov_b64_e32 v[54:55], 0
	v_mov_b64_e32 v[56:57], 0
	v_mov_b64_e32 v[58:59], 0
	v_mov_b64_e32 v[60:61], 0
	v_mov_b64_e32 v[62:63], 0
	v_mov_b64_e32 v[64:65], 0
	v_mov_b64_e32 v[66:67], 0
	v_mov_b64_e32 v[68:69], 0
	v_mov_b64_e32 v[70:71], 0
	v_mov_b64_e32 v[72:73], 0
	v_mov_b64_e32 v[74:75], 0
	v_mov_b64_e32 v[76:77], 0
	v_mov_b64_e32 v[78:79], 0
	v_mov_b64_e32 v[80:81], 0
	v_mov_b64_e32 v[82:83], 0
	v_mov_b64_e32 v[84:85], 0
	v_mov_b64_e32 v[86:87], 0
	v_mov_b64_e32 v[88:89], 0
	v_mov_b64_e32 v[90:91], 0
	v_mov_b64_e32 v[92:93], 0
	v_mov_b64_e32 v[94:95], 0
	v_mov_b64_e32 v[96:97], 0
	v_mov_b64_e32 v[98:99], 0
	v_mov_b64_e32 v[100:101], 0
	v_mov_b64_e32 v[102:103], 0
	v_mov_b64_e32 v[104:105], 0
	v_mov_b64_e32 v[106:107], 0
	v_mov_b64_e32 v[108:109], 0
	v_mov_b64_e32 v[110:111], 0
	v_mov_b64_e32 v[112:113], 0
	v_mov_b64_e32 v[114:115], 0
	v_mov_b64_e32 v[116:117], 0
	v_mov_b64_e32 v[118:119], 0
	v_mov_b64_e32 v[120:121], 0
	v_mov_b64_e32 v[122:123], 0
	v_mov_b64_e32 v[124:125], 0
	v_mov_b64_e32 v[126:127], 0
	s_barrier
	s_barrier
